# peeled first tile of each attention unit: no longer drains all DMA tiles (vmcnt(0)) before its first MFMA / first V read; upproj kv gains grouped
# speedup vs baseline: 1.0024x; 1.0024x over previous
; template <int DQK, int DV, int NKH, int MODE>
; DEV void flash_unit(const FlashArgs& fa, char* smem, f32x16 (&oacc)[DV / 32], float& linv_out) {
;     ...
;   bf16x8 qf[NS];
;   {
;     const u16* qp = (kh ? fa.Q1 : fa.Q0) + (size_t)(fa.q_t0 + qsub * 32 + r) * DQK + 8 * h;
; #pragma unroll
;     for (int s = 0; s < NS; ++s) qf[s] = *(const bf16x8*)(qp + 16 * s);
;     ...
;   asm volatile("s_waitcnt vmcnt(0)" ::: "memory");
;   issue(0);
;   issue(1);
;   issue(2);
;   for (int it = 0; it < fa.n_tiles; ++it) {
;     {
;       const int newer = min(2, fa.n_tiles - 1 - it) * nld;
;       if (newer >= 8) asm volatile("s_waitcnt vmcnt(8)" ::: "memory");
;       else if (newer == 6) asm volatile("s_waitcnt vmcnt(6)" ::: "memory");
;       else if (newer == 4) asm volatile("s_waitcnt vmcnt(4)" ::: "memory");
;       else if (newer == 3) asm volatile("s_waitcnt vmcnt(3)" ::: "memory");
;       else if (newer == 2) asm volatile("s_waitcnt vmcnt(2)" ::: "memory");
;       else asm volatile("s_waitcnt vmcnt(0)" ::: "memory");
;     }
;     __builtin_amdgcn_s_barrier();
;     const bool pre = (it + 3 < fa.n_tiles);
;     bool active = true;
;     int krow = 0;
;     if (MODE == 1 && it >= 4) {
;       krow = tile_id(it) - 4;
;       active = (krow >= na_rs) && (krow < na_rs + 8);
;     }
;     if (active) {
;       const char* sb = smem + (it & (NSTG - 1)) * STAGE;
;       const char* kb = sb + kh * 8192 + r * 128;
;       const char* kb32 = sb + OFF_K32 + r * 64;
;       const char* vb = sb + OFF_V;
;       f32x16 st[2];
;       bf16x8 kfr[2][NS];
; #pragma unroll
;       for (int k2 = 0; k2 < 2; ++k2)
; #pragma unroll
;         for (int s = 0; s < NS; ++s) {
;           if (s < 4) kfr[k2][s] = *(const bf16x8*)(kb + k2 * 32 * 128 + kxo[s]);
;           else kfr[k2][s] = *(const bf16x8*)(kb32 + k2 * 32 * 64 + (((2 * (s - 4) + h) ^ k32x) << 4));
;         }
;       __builtin_amdgcn_sched_barrier(0);
.LBB0_71:
	s_or_b64 exec, exec, s[2:3]
	v_lshlrev_b32_e32 v16, 10, v4
	v_lshlrev_b32_e32 v4, 5, v4
	v_and_b32_e32 v15, 31, v2
	s_movk_i32 s2, 0x100
	v_and_b32_e32 v4, 0x60, v4
	s_add_u32 s0, s38, s0
	v_cmp_gt_u32_e32 vcc, s2, v2
	v_add3_u32 v12, v15, s9, v4
	s_addc_u32 s1, s39, s1
	v_cndmask_b32_e64 v10, v174, 0, vcc
	v_mov_b32_e32 v11, v145
	v_ashrrev_i32_e32 v13, 31, v12
	v_lshrrev_b32_e32 v14, 5, v3
	v_lshl_add_u64 v[10:11], s[0:1], 0, v[10:11]
	v_lshlrev_b64 v[12:13], 7, v[12:13]
	v_lshl_add_u64 v[10:11], v[10:11], 0, v[12:13]
	v_lshlrev_b32_e32 v12, 4, v14
	v_mov_b32_e32 v13, v145
	v_lshl_add_u64 v[10:11], v[10:11], 0, v[12:13]
	s_mov_b64 s[0:1], 0xbcd6100
	v_lshl_add_u64 v[12:13], v[10:11], 0, s[0:1]
	s_mov_b32 s0, 0xbcd6000
	v_add3_u32 v183, 0, v16, v5
	v_mov_b32_e32 v99, v145
	v_add_co_u32_e32 v10, vcc, s0, v10
	v_readfirstlane_b32 s0, v183
	v_add_u32_e32 v4, 0x2000, v183
	v_mov_b32_e32 v103, v145
	v_lshl_add_u64 v[8:9], v[96:97], 0, v[98:99]
	v_addc_co_u32_e32 v11, vcc, 0, v11, vcc
	flat_load_dwordx4 v[112:115], v[12:13] offset:32
	flat_load_dwordx4 v[116:119], v[12:13] offset:64
	flat_load_dwordx4 v[120:123], v[10:11] offset:256
	flat_load_dwordx4 v[124:127], v[12:13] offset:96
	s_waitcnt vmcnt(0)
	s_mov_b32 m0, s0
	v_readfirstlane_b32 s0, v4
	v_add_u32_e32 v4, 0x4000, v183
	v_lshl_add_u64 v[6:7], v[100:101], 0, v[102:103]
	global_load_lds_dwordx4 v[8:9], off
	s_mov_b32 m0, s0
	v_readfirstlane_b32 s0, v4
	v_add_u32_e32 v4, 0x6000, v183
	v_lshl_add_u64 v[0:1], v[104:105], 0, v[144:145]
	v_mov_b32_e32 v109, v145
	global_load_lds_dwordx4 v[6:7], off
	s_mov_b32 m0, s0
	v_readfirstlane_b32 s0, v4
	v_add_u32_e32 v12, 0x8000, v183
	v_lshl_add_u64 v[10:11], v[106:107], 0, v[108:109]
	global_load_lds_dwordx4 v[0:1], off
	s_mov_b32 m0, s0
	v_lshl_add_u64 v[4:5], v[8:9], 0, v[148:149]
	v_readfirstlane_b32 s0, v12
	v_add_u32_e32 v8, 0xa000, v183
	global_load_lds_dwordx4 v[10:11], off
	s_mov_b32 m0, s0
	v_readfirstlane_b32 s0, v8
	v_add_u32_e32 v8, 0xc000, v183
	global_load_lds_dwordx4 v[4:5], off
	v_lshl_add_u64 v[6:7], v[6:7], 0, v[150:151]
	s_mov_b32 m0, s0
	v_readfirstlane_b32 s0, v8
	v_add_u32_e32 v12, 0xe000, v183
	global_load_lds_dwordx4 v[6:7], off
	v_lshl_add_u64 v[0:1], v[0:1], 0, v[152:153]
	s_mov_b32 m0, s0
	v_lshl_add_u64 v[8:9], v[10:11], 0, v[154:155]
	v_readfirstlane_b32 s0, v12
	v_add_u32_e32 v10, 0x10000, v183
	global_load_lds_dwordx4 v[0:1], off
	s_mov_b32 m0, s0
	v_lshl_add_u64 v[44:45], v[4:5], 0, v[148:149]
	v_readfirstlane_b32 s0, v10
	v_add_u32_e32 v4, 0x12000, v183
	global_load_lds_dwordx4 v[8:9], off
	s_mov_b32 m0, s0
	v_readfirstlane_b32 s0, v4
	v_add_u32_e32 v4, 0x14000, v183
	global_load_lds_dwordx4 v[44:45], off
	v_lshl_add_u64 v[46:47], v[6:7], 0, v[150:151]
	s_mov_b32 m0, s0
	v_lshl_add_u64 v[48:49], v[0:1], 0, v[152:153]
	v_readfirstlane_b32 s0, v4
	v_add_u32_e32 v0, 0x16000, v183
	global_load_lds_dwordx4 v[46:47], off
	s_mov_b32 m0, s0
	v_readfirstlane_b32 s0, v0
	global_load_lds_dwordx4 v[48:49], off
	v_lshl_add_u64 v[50:51], v[8:9], 0, v[154:155]
	s_mov_b32 m0, s0
	v_lshrrev_b32_e32 v0, 1, v2
	global_load_lds_dwordx4 v[50:51], off
	v_bitop3_b32 v0, v14, v0, 7 bitop3:0x78
	v_lshrrev_b32_e32 v5, 3, v2
	v_lshlrev_b32_e32 v184, 4, v0
	v_or_b32_e32 v0, 2, v14
	v_and_b32_e32 v5, 2, v5
	v_bfe_u32 v6, v2, 1, 1
	v_bfe_u32 v1, v2, 1, 3
	v_bitop3_b32 v7, v5, v14, v6 bitop3:0x36
	v_bitop3_b32 v5, v5, v0, v6 bitop3:0x36
	v_lshlrev_b32_e32 v0, 5, v2
	v_bitop3_b32 v4, v14, v1, 2 bitop3:0x36
	v_and_b32_e32 v192, 0xffffe000, v0
	v_lshlrev_b32_e32 v193, 7, v15
	v_lshlrev_b32_e32 v185, 4, v4
	v_bitop3_b32 v4, v14, v1, 4 bitop3:0x36
	v_bitop3_b32 v1, v14, v1, 6 bitop3:0x36
	v_add3_u32 v0, 0, v192, v193
	v_lshlrev_b32_e32 v186, 4, v4
	v_lshlrev_b32_e32 v187, 4, v1
	v_bfe_u32 v1, v2, 2, 2
	v_add_u32_e32 v6, v0, v184
	v_lshlrev_b32_e32 v4, 8, v1
	v_lshlrev_b32_e32 v8, 3, v3
	v_lshlrev_b32_e32 v188, 6, v1
	s_waitcnt vmcnt(8)
	s_barrier
	v_add_u32_e32 v9, v0, v185
	v_add_u32_e32 v10, v0, v186
	v_add_u32_e32 v11, v0, v187
	ds_read_b128 v[0:3], v6
	ds_read_b128 v[16:19], v6 offset:4096
	ds_read_b128 v[20:23], v9
	ds_read_b128 v[32:35], v9 offset:4096
	ds_read_b128 v[24:27], v10
	ds_read_b128 v[36:39], v10 offset:4096
	ds_read_b128 v[28:31], v11
	ds_read_b128 v[40:43], v11 offset:4096
	s_mov_b32 s17, 0
	s_mov_b32 s4, 4
	v_xor_b32_e32 v189, 64, v188
	v_xor_b32_e32 v190, 0x80, v188
	v_xor_b32_e32 v191, 0xc0, v188
	v_lshl_or_b32 v194, v14, 10, v4
	v_lshlrev_b32_e32 v195, 4, v7
	v_and_b32_e32 v196, 8, v8
	v_lshlrev_b32_e32 v197, 4, v5
	s_waitcnt lgkmcnt(0)
	v_mfma_f32_32x32x16_bf16 v[0:15], v[0:3], v[120:123], 0
	v_add_u32_e32 v52, 0x1e000, v183
	v_add_u32_e32 v53, 0x1c000, v183
	v_add_u32_e32 v54, 0x1a000, v183
	v_mfma_f32_32x32x16_bf16 v[0:15], v[20:23], v[112:115], v[0:15]
	v_add_u32_e32 v22, 0x18000, v183
	v_lshl_add_u64 v[20:21], v[44:45], 0, v[148:149]
	v_readfirstlane_b32 s0, v22
	s_mov_b32 m0, s0
	s_nop 0
	global_load_lds_dwordx4 v[20:21], off
	v_mfma_f32_32x32x16_bf16 v[0:15], v[24:27], v[116:119], v[0:15]
	v_mfma_f32_32x32x16_bf16 v[0:15], v[28:31], v[124:127], v[0:15]
	v_readfirstlane_b32 s0, v54
	v_lshl_add_u64 v[20:21], v[46:47], 0, v[150:151]
	s_mov_b32 m0, s0
	s_nop 0
	global_load_lds_dwordx4 v[20:21], off
	v_mfma_f32_32x32x16_bf16 v[16:31], v[16:19], v[120:123], 0
	v_mfma_f32_32x32x16_bf16 v[16:31], v[32:35], v[112:115], v[16:31]
	v_readfirstlane_b32 s0, v53
	v_lshl_add_u64 v[32:33], v[48:49], 0, v[152:153]
	s_mov_b32 m0, s0
	s_nop 0
	global_load_lds_dwordx4 v[32:33], off
	v_mfma_f32_32x32x16_bf16 v[16:31], v[36:39], v[116:119], v[16:31]
	v_mfma_f32_32x32x16_bf16 v[16:31], v[40:43], v[124:127], v[16:31]
	v_readfirstlane_b32 s0, v52
	v_lshl_add_u64 v[32:33], v[50:51], 0, v[154:155]
	s_mov_b32 m0, s0
	s_nop 0
	global_load_lds_dwordx4 v[32:33], off
	v_max_f32_e32 v32, v1, v1
	v_max_f32_e32 v33, v0, v0
	v_max_f32_e32 v32, v33, v32
	v_max3_f32 v32, v32, v2, v3
	v_max3_f32 v32, v32, v4, v5
	v_max3_f32 v32, v32, v6, v7
	v_max3_f32 v32, v32, v8, v9
	v_max3_f32 v32, v32, v10, v11
	v_max3_f32 v32, v32, v12, v13
	v_max3_f32 v32, v32, v14, v15
	v_max3_f32 v32, v32, v16, v17
	v_max3_f32 v32, v32, v18, v19
	v_max3_f32 v32, v32, v20, v21
	v_max3_f32 v32, v32, v22, v23
	v_max3_f32 v32, v32, v24, v25
	v_max3_f32 v32, v32, v26, v27
	v_max3_f32 v32, v32, v28, v29
	v_max3_f32 v32, v32, v30, v31
	v_mov_b32_e32 v33, v32
	s_nop 1
	v_permlane32_swap_b32_e32 v32, v33
	v_max_f32_e32 v33, v33, v33
	v_max_f32_e32 v32, v32, v32
	v_max_f32_e32 v110, v32, v33
	v_sub_f32_e32 v0, v0, v110
	v_sub_f32_e32 v4, v4, v110
	v_exp_f32_e32 v111, v0
	v_add3_u32 v0, 0, v188, v194
	v_exp_f32_e64 v32, -v110
	v_sub_f32_e32 v1, v1, v110
	v_sub_f32_e32 v2, v2, v110
	v_sub_f32_e32 v3, v3, v110
	v_sub_f32_e32 v5, v5, v110
	v_sub_f32_e32 v6, v6, v110
	v_sub_f32_e32 v7, v7, v110
	v_exp_f32_e32 v131, v4
	v_add3_u32 v4, v0, v195, v196
	v_exp_f32_e32 v128, v1
	v_exp_f32_e32 v129, v2
	v_exp_f32_e32 v130, v3
	v_exp_f32_e32 v132, v5
	v_exp_f32_e32 v133, v6
	v_exp_f32_e32 v134, v7
	v_add3_u32 v5, v0, v197, v196
	ds_read_b64_tr_b16 v[0:1], v4 offset:16384
	ds_read_b64_tr_b16 v[2:3], v5 offset:18432
	v_mul_f32_e32 v64, 0, v32
	v_mov_b32_e32 v65, v64
	v_mov_b32_e32 v66, v64
	v_mov_b32_e32 v67, v64
	v_mov_b32_e32 v68, v64
	v_mov_b32_e32 v69, v64
	v_mov_b32_e32 v70, v64
	v_mov_b32_e32 v71, v64
	v_mov_b32_e32 v72, v64
	v_mov_b32_e32 v73, v64
	v_mov_b32_e32 v74, v64
	v_mov_b32_e32 v75, v64
	v_mov_b32_e32 v76, v64
	v_mov_b32_e32 v77, v64
	v_mov_b32_e32 v78, v64
	v_mov_b32_e32 v79, v64
	v_cvt_pk_bf16_f32 v92, v111, v128
	v_cvt_pk_bf16_f32 v93, v129, v130
	v_cvt_pk_bf16_f32 v94, v131, v132
	v_cvt_pk_bf16_f32 v95, v133, v134
	v_sub_f32_e32 v8, v8, v110
	v_sub_f32_e32 v9, v9, v110
	s_waitcnt lgkmcnt(0)
	v_mfma_f32_32x32x16_bf16 v[32:47], v[0:3], v[92:95], v[64:79]
	v_sub_f32_e32 v10, v10, v110
	v_sub_f32_e32 v11, v11, v110
	v_sub_f32_e32 v12, v12, v110
	v_sub_f32_e32 v13, v13, v110
	v_sub_f32_e32 v14, v14, v110
	v_sub_f32_e32 v15, v15, v110
	v_exp_f32_e32 v135, v8
	v_exp_f32_e32 v136, v9
	v_exp_f32_e32 v137, v10
	v_exp_f32_e32 v138, v11
	v_exp_f32_e32 v139, v12
	v_exp_f32_e32 v140, v13
	v_exp_f32_e32 v141, v14
	v_exp_f32_e32 v142, v15
	ds_read_b64_tr_b16 v[0:1], v4 offset:20480
	ds_read_b64_tr_b16 v[2:3], v5 offset:22528
	v_cvt_pk_bf16_f32 v88, v135, v136
	v_cvt_pk_bf16_f32 v89, v137, v138
	v_cvt_pk_bf16_f32 v90, v139, v140
	v_cvt_pk_bf16_f32 v91, v141, v142
	v_sub_f32_e32 v16, v16, v110
	v_sub_f32_e32 v17, v17, v110
	s_waitcnt lgkmcnt(0)
	v_mfma_f32_32x32x16_bf16 v[32:47], v[0:3], v[88:91], v[32:47]
	v_sub_f32_e32 v18, v18, v110
	v_sub_f32_e32 v19, v19, v110
	v_sub_f32_e32 v20, v20, v110
	v_sub_f32_e32 v21, v21, v110
	v_sub_f32_e32 v22, v22, v110
	v_sub_f32_e32 v23, v23, v110
	v_exp_f32_e32 v143, v16
	v_exp_f32_e32 v156, v17
	v_exp_f32_e32 v157, v18
	v_exp_f32_e32 v158, v19
	v_exp_f32_e32 v159, v20
	v_exp_f32_e32 v160, v21
	v_exp_f32_e32 v161, v22
	v_exp_f32_e32 v162, v23
	ds_read_b64_tr_b16 v[0:1], v4 offset:24576
	ds_read_b64_tr_b16 v[2:3], v5 offset:26624
	v_cvt_pk_bf16_f32 v84, v143, v156
	v_cvt_pk_bf16_f32 v85, v157, v158
	v_cvt_pk_bf16_f32 v86, v159, v160
	v_cvt_pk_bf16_f32 v87, v161, v162
	v_sub_f32_e32 v24, v24, v110
	v_sub_f32_e32 v25, v25, v110
	s_waitcnt lgkmcnt(0)
	v_mfma_f32_32x32x16_bf16 v[32:47], v[0:3], v[84:87], v[32:47]
	v_sub_f32_e32 v26, v26, v110
	v_sub_f32_e32 v27, v27, v110
	v_sub_f32_e32 v28, v28, v110
	v_sub_f32_e32 v29, v29, v110
	v_sub_f32_e32 v30, v30, v110
	v_sub_f32_e32 v31, v31, v110
	v_exp_f32_e32 v163, v24
	v_exp_f32_e32 v164, v25
	v_exp_f32_e32 v165, v26
	v_exp_f32_e32 v198, v27
	v_exp_f32_e32 v199, v28
	v_exp_f32_e32 v200, v29
	v_exp_f32_e32 v201, v30
	v_exp_f32_e32 v202, v31
	ds_read_b64_tr_b16 v[0:1], v4 offset:28672
	ds_read_b64_tr_b16 v[2:3], v5 offset:30720
	v_cvt_pk_bf16_f32 v80, v163, v164
	v_cvt_pk_bf16_f32 v81, v165, v198
	v_cvt_pk_bf16_f32 v82, v199, v200
	v_cvt_pk_bf16_f32 v83, v201, v202
	s_lshl_b32 s13, s11, 15
	s_add_i32 s5, s13, 0xffff8000
	s_waitcnt lgkmcnt(0)
; #define MFMA(a, b, c) __builtin_amdgcn_mfma_f32_32x32x16_bf16((a), (b), (c), 0, 0, 0)
; DEV float fast_exp2(float x) { return __builtin_amdgcn_exp2f(x); }
; template <int DQK, int DV, int NKH, int MODE>
; DEV void flash_unit(const FlashArgs& fa, char* smem, f32x16 (&oacc)[DV / 32], float& linv_out) {
;     ...
;         for (int v = 0; v < NV; ++v)
; #pragma unroll
;           for (int e = 0; e < 16; ++e) oacc[v][e] *= alpha;
; #pragma unroll
;         for (int e = 0; e < 16; ++e) negm[e] = -mrun;
;         lrun *= alpha;
;       }
;       float psum = 0.f;
; #pragma unroll
;       for (int k2 = 0; k2 < 2; ++k2)
; #pragma unroll
;         for (int e = 0; e < 16; ++e) { st[k2][e] = fast_exp2(st[k2][e]); psum += st[k2][e]; }
;       lrun += psum;
;       bf16x8 pf[2][2];
; #pragma unroll
;       for (int k2 = 0; k2 < 2; ++k2)
; #pragma unroll
;         for (int s2 = 0; s2 < 2; ++s2) {
;           uint4 u = make_uint4(pk2(st[k2][8 * s2], st[k2][8 * s2 + 1]), pk2(st[k2][8 * s2 + 2], st[k2][8 * s2 + 3]),
;                                pk2(st[k2][8 * s2 + 4], st[k2][8 * s2 + 5]), pk2(st[k2][8 * s2 + 6], st[k2][8 * s2 + 7]));
;           pf[k2][s2] = __builtin_bit_cast(bf16x8, u);
;         }
; #pragma unroll
;       for (int v = 0; v < NV; ++v)
; #pragma unroll
;         for (int k2 = 0; k2 < 2; ++k2)
; #pragma unroll
;           for (int s2 = 0; s2 < 2; ++s2) {
;             const char* a1 = vb + (k2 * 32 + s2 * 16) * VROW + vhi[v] + vlow0;
;             const char* a2 = vb + (k2 * 32 + s2 * 16 + 8) * VROW + vhi[v] + vlow1;
;             s16x4 lo = __builtin_amdgcn_ds_read_tr16_b64_v4i16((__attribute__((address_space(3))) s16x4*)(a1));
;             s16x4 hi = __builtin_amdgcn_ds_read_tr16_b64_v4i16((__attribute__((address_space(3))) s16x4*)(a2));
;             const bf16x8 vf = __builtin_shufflevector(lo, hi, 0, 1, 2, 3, 4, 5, 6, 7);
;             oacc[v] = MFMA(vf, pf[k2][s2], oacc[v]);
;           }
	v_mfma_f32_32x32x16_bf16 v[32:47], v[0:3], v[80:83], v[32:47]
	v_add3_u32 v0, 0, v189, v194
	v_add3_u32 v4, v0, v195, v196
	v_add3_u32 v5, v0, v197, v196
	ds_read_b64_tr_b16 v[0:1], v4 offset:16384
	ds_read_b64_tr_b16 v[2:3], v5 offset:18432
	s_add_i32 s13, s13, 0xfffe8000
	s_add_i32 s14, s11, -2
	s_waitcnt lgkmcnt(0)
	v_mfma_f32_32x32x16_bf16 v[48:63], v[0:3], v[92:95], v[64:79]
	ds_read_b64_tr_b16 v[0:1], v4 offset:20480
	ds_read_b64_tr_b16 v[2:3], v5 offset:22528
	s_waitcnt lgkmcnt(0)
	v_mfma_f32_32x32x16_bf16 v[48:63], v[0:3], v[88:91], v[48:63]
	ds_read_b64_tr_b16 v[0:1], v4 offset:24576
	ds_read_b64_tr_b16 v[2:3], v5 offset:26624
	s_waitcnt lgkmcnt(0)
	v_mfma_f32_32x32x16_bf16 v[48:63], v[0:3], v[84:87], v[48:63]
	ds_read_b64_tr_b16 v[0:1], v4 offset:28672
	ds_read_b64_tr_b16 v[2:3], v5 offset:30720
	s_waitcnt lgkmcnt(0)
	v_mfma_f32_32x32x16_bf16 v[48:63], v[0:3], v[80:83], v[48:63]
	v_add3_u32 v0, 0, v190, v194
	v_add3_u32 v4, v0, v195, v196
	v_add3_u32 v5, v0, v197, v196
	ds_read_b64_tr_b16 v[0:1], v4 offset:16384
	ds_read_b64_tr_b16 v[2:3], v5 offset:18432
	s_waitcnt lgkmcnt(0)
	v_mfma_f32_32x32x16_bf16 v[16:31], v[0:3], v[92:95], v[64:79]
	ds_read_b64_tr_b16 v[0:1], v4 offset:20480
	ds_read_b64_tr_b16 v[2:3], v5 offset:22528
	s_waitcnt lgkmcnt(0)
	v_mfma_f32_32x32x16_bf16 v[16:31], v[0:3], v[88:91], v[16:31]
	ds_read_b64_tr_b16 v[0:1], v4 offset:24576
	ds_read_b64_tr_b16 v[2:3], v5 offset:26624
	s_waitcnt lgkmcnt(0)
	v_mfma_f32_32x32x16_bf16 v[16:31], v[0:3], v[84:87], v[16:31]
	ds_read_b64_tr_b16 v[0:1], v4 offset:28672
	ds_read_b64_tr_b16 v[2:3], v5 offset:30720
	s_waitcnt lgkmcnt(0)
	v_mfma_f32_32x32x16_bf16 v[16:31], v[0:3], v[80:83], v[16:31]
	v_add3_u32 v0, 0, v191, v194
	v_add3_u32 v203, v0, v195, v196
	v_add3_u32 v208, v0, v197, v196
	v_mov_b64_e32 v[0:1], v[64:65]
	v_mov_b64_e32 v[2:3], v[66:67]
	v_mov_b64_e32 v[4:5], v[68:69]
	v_mov_b64_e32 v[6:7], v[70:71]
	v_mov_b64_e32 v[8:9], v[72:73]
	v_mov_b64_e32 v[10:11], v[74:75]
	v_mov_b64_e32 v[12:13], v[76:77]
	v_mov_b64_e32 v[14:15], v[78:79]
	v_add_f32_e32 v65, 0, v111
	v_add_f32_e32 v65, v128, v65
	ds_read_b64_tr_b16 v[204:205], v203 offset:16384
	ds_read_b64_tr_b16 v[206:207], v208 offset:18432
	v_add_f32_e32 v65, v129, v65
	v_add_f32_e32 v65, v130, v65
	v_add_f32_e32 v65, v131, v65
	v_add_f32_e32 v65, v132, v65
	v_add_f32_e32 v65, v133, v65
	s_waitcnt lgkmcnt(0)
	v_mfma_f32_32x32x16_bf16 v[0:15], v[204:207], v[92:95], v[0:15]
	v_add_f32_e32 v65, v134, v65
	v_add_f32_e32 v65, v135, v65
	v_add_f32_e32 v65, v136, v65
	ds_read_b64_tr_b16 v[66:67], v203 offset:20480
	ds_read_b64_tr_b16 v[68:69], v208 offset:22528
	v_add_f32_e32 v65, v137, v65
	v_add_f32_e32 v65, v138, v65
	v_add_f32_e32 v65, v139, v65
	v_add_f32_e32 v65, v140, v65
	v_add_f32_e32 v65, v141, v65
	s_waitcnt lgkmcnt(0)
	v_mfma_f32_32x32x16_bf16 v[0:15], v[66:69], v[88:91], v[0:15]
	v_add_f32_e32 v65, v142, v65
	v_add_f32_e32 v65, v143, v65
	v_add_f32_e32 v65, v156, v65
	ds_read_b64_tr_b16 v[66:67], v203 offset:24576
	ds_read_b64_tr_b16 v[68:69], v208 offset:26624
	v_add_f32_e32 v65, v157, v65
	v_add_f32_e32 v65, v158, v65
	v_add_f32_e32 v65, v159, v65
	v_add_f32_e32 v65, v160, v65
	v_add_f32_e32 v65, v161, v65
	s_waitcnt lgkmcnt(0)
	v_mfma_f32_32x32x16_bf16 v[0:15], v[66:69], v[84:87], v[0:15]
	v_add_f32_e32 v65, v162, v65
	v_add_f32_e32 v65, v163, v65
	v_add_f32_e32 v65, v164, v65
	ds_read_b64_tr_b16 v[66:67], v203 offset:28672
	ds_read_b64_tr_b16 v[68:69], v208 offset:30720
	v_add_f32_e32 v65, v165, v65
	v_add_f32_e32 v65, v198, v65
	v_add_f32_e32 v65, v199, v65
	v_add_f32_e32 v65, v200, v65
	v_add_f32_e32 v65, v201, v65
	s_waitcnt lgkmcnt(0)
	v_mfma_f32_32x32x16_bf16 v[0:15], v[66:69], v[80:83], v[0:15]
	v_add_f32_e32 v66, v202, v65
	v_mov_b32_e32 v65, v110
	v_mov_b32_e32 v67, v145
	v_add_f32_e64 v156, v64, v66
	v_add_f32_e64 v157, v65, v67
	v_lshlrev_b32_e32 v66, 2, v154
	v_lshl_add_u64 v[66:67], v[66:67], 0, v[108:109]
	v_lshl_add_u64 v[158:159], v[106:107], 0, v[66:67]
	v_lshlrev_b32_e32 v66, 2, v152
	v_mov_b32_e32 v67, v145
	v_lshl_add_u64 v[66:67], v[66:67], 0, v[144:145]
	v_lshlrev_b32_e32 v144, 2, v150
	v_lshl_add_u64 v[160:161], v[104:105], 0, v[66:67]
	v_lshl_add_u64 v[66:67], v[144:145], 0, v[102:103]
	v_lshlrev_b32_e32 v144, 2, v148
	v_xor_b32_e32 v64, 0x80000000, v157
	v_lshl_add_u64 v[162:163], v[100:101], 0, v[66:67]
	v_lshl_add_u64 v[66:67], v[144:145], 0, v[98:99]
	v_lshl_add_u64 v[164:165], v[96:97], 0, v[66:67]
	v_mov_b32_e32 v65, v64
	v_mov_b32_e32 v66, v64
	v_mov_b32_e32 v67, v64
	v_mov_b32_e32 v68, v64
	v_mov_b32_e32 v69, v64
	v_mov_b32_e32 v70, v64
	v_mov_b32_e32 v71, v64
	v_mov_b32_e32 v72, v64
	v_mov_b32_e32 v73, v64
	v_mov_b32_e32 v74, v64
	v_mov_b32_e32 v75, v64
	v_mov_b32_e32 v76, v64
	v_mov_b32_e32 v77, v64
	v_mov_b32_e32 v78, v64
	v_mov_b32_e32 v79, v64
	s_cmp_lt_i32 s14, 2
	s_mov_b64 s[0:1], -1
	s_cbranch_scc0 .LBB0_78
	s_branch .LBB0_73

; template <int DQK, int DV, int NKH, int MODE>
; DEV void flash_unit(const FlashArgs& fa, char* smem, f32x16 (&oacc)[DV / 32], float& linv_out) {
;     ...
; #pragma unroll
;       for (int k2 = 0; k2 < 2; ++k2)
; #pragma unroll
;         for (int s = 0; s < NS; ++s) {
;           if (s < 4) kfr[k2][s] = *(const bf16x8*)(kb + k2 * 32 * 128 + kxo[s]);
;           else kfr[k2][s] = *(const bf16x8*)(kb32 + k2 * 32 * 64 + (((2 * (s - 4) + h) ^ k32x) << 4));
;         }
;       __builtin_amdgcn_sched_barrier(0);
; #pragma unroll
;       for (int k2 = 0; k2 < 2; ++k2) {
; #pragma unroll
;         for (int s = 0; s < NS; ++s) {
;           const bf16x8 kf = kfr[k2][s];
;           if (s == 0) st[k2] = MFMA(kf, qf[s], negm);
;           else st[k2] = MFMA(kf, qf[s], st[k2]);
;           constexpr int NQK = 2 * NS, EVERY = NQK / LPT;
;           const int m = k2 * NS + s;
;           if ((m + 1) % EVERY == 0 && (m + 1) / EVERY <= LPT) {
;             __builtin_amdgcn_sched_barrier(0);
;             if (pre) issue_piece(it + 3, (m + 1) / EVERY - 1);
;             __builtin_amdgcn_sched_barrier(0);
;           }
;         }
;       }
;       if (MODE == 1 && it >= 4) {
;         const int dr = krow - na_row + 7;
;         const float* bp = rpbs + dr * 31;
; #pragma unroll
;         for (int k2 = 0; k2 < 2; ++k2)
; #pragma unroll
;           for (int e = 0; e < 16; ++e) {
;             const int kc = k2 * 32 + crow_of(e, h);
;             const bool valid = (kc >= na_cstart) && (kc < na_cstart + 16);
;             const int idx = min(max(kc - na_qc + 15, 0), 30);
;             const float bv = bp[idx];
;             st[k2][e] = valid ? st[k2][e] + bv : -1e30f;
;           }
;       }
;       float rel = st[0][0];
; #pragma unroll
;       for (int e = 1; e < 16; ++e) rel = fmaxf(rel, st[0][e]);
; #pragma unroll
;       for (int e = 0; e < 16; ++e) rel = fmaxf(rel, st[1][e]);
;       rel = half_max(rel);
;       const bool first = (it == 0);
;       if (first || __builtin_amdgcn_ballot_w64(rel > 8.f) != 0) {
;         const float d = first ? rel : fmaxf(rel, 0.f);
;         const float alpha = fast_exp2(-d);
;         mrun += d;
; #pragma unroll
;         for (int k2 = 0; k2 < 2; ++k2)
; #pragma unroll
;           for (int e = 0; e < 16; ++e) st[k2][e] -= d;
; #pragma unroll
;         for (int v = 0; v < NV; ++v)
; #pragma unroll
.LBB0_167:
	s_or_b64 exec, exec, s[2:3]
	v_lshrrev_b32_e32 v0, 2, v37
	v_bfe_u32 v39, v37, 2, 2
	v_bitop3_b32 v0, v38, v0, 3 bitop3:0x78
	v_lshlrev_b32_e32 v149, 4, v0
	v_bitop3_b32 v0, v38, v39, 2 bitop3:0x36
	v_lshrrev_b32_e32 v40, 1, v37
	v_lshlrev_b32_e32 v150, 4, v0
	v_bfe_u32 v0, v37, 1, 3
	v_bitop3_b32 v1, v38, v40, 7 bitop3:0x78
	v_lshlrev_b32_e32 v151, 4, v1
	v_bitop3_b32 v1, v38, v0, 2 bitop3:0x36
	v_lshlrev_b32_e32 v146, 7, v8
	v_lshlrev_b32_e32 v152, 4, v1
	v_bitop3_b32 v1, v38, v0, 4 bitop3:0x36
	v_bitop3_b32 v0, v38, v0, 6 bitop3:0x36
	v_lshlrev_b32_e32 v148, 6, v8
	v_lshlrev_b32_e32 v154, 4, v0
	v_add_u32_e32 v0, 0, v146
	v_lshlrev_b32_e32 v153, 4, v1
	v_sub_u32_e32 v1, v0, v148
	v_add_u32_e32 v4, v0, v151
	s_barrier
	v_add_u32_e32 v5, v0, v152
	v_add_u32_e32 v6, v0, v153
	v_add_u32_e32 v7, v0, v154
	v_add_u32_e32 v8, v1, v149
	v_add_u32_e32 v9, v1, v150
	ds_read_b128 v[0:3], v4
	ds_read_b128 v[18:21], v4 offset:4096
	ds_read_b128 v[22:25], v5
	ds_read_b128 v[42:45], v5 offset:4096
	ds_read_b128 v[26:29], v6
	ds_read_b128 v[46:49], v6 offset:4096
	ds_read_b128 v[50:53], v7
	ds_read_b128 v[54:57], v7 offset:4096
	ds_read_b128 v[58:61], v8 offset:8192
	ds_read_b128 v[74:77], v8 offset:10240
	ds_read_b128 v[104:107], v9 offset:8192
	ds_read_b128 v[108:111], v9 offset:10240
	s_waitcnt lgkmcnt(0)
	v_mfma_f32_32x32x16_bf16 v[0:15], v[0:3], v[80:83], 0
	v_add_u32_e32 v41, 0x11000, v143
	v_mfma_f32_32x32x16_bf16 v[0:15], v[22:25], v[84:87], v[0:15]
	v_mfma_f32_32x32x16_bf16 v[0:15], v[26:29], v[88:91], v[0:15]
	v_mfma_f32_32x32x16_bf16 v[0:15], v[50:53], v[92:95], v[0:15]
	v_add_u32_e32 v22, 0xf000, v143
	v_lshl_add_u64 v[16:17], v[16:17], 0, v[128:129]
	v_readfirstlane_b32 s2, v22
	s_mov_b32 m0, s2
	s_nop 0
	global_load_lds_dwordx4 v[16:17], off
	v_mfma_f32_32x32x16_bf16 v[0:15], v[58:61], v[96:99], v[0:15]
	v_mfma_f32_32x32x16_bf16 v[16:31], v[18:21], v[80:83], 0
	v_mfma_f32_32x32x16_bf16 v[0:15], v[104:107], v[100:103], v[0:15]
	v_mfma_f32_32x32x16_bf16 v[16:31], v[42:45], v[84:87], v[16:31]
	v_readfirstlane_b32 s2, v41
	v_lshl_add_u64 v[34:35], v[34:35], 0, v[130:131]
	s_mov_b32 m0, s2
	s_nop 0
	global_load_lds_dwordx4 v[34:35], off
	v_mfma_f32_32x32x16_bf16 v[16:31], v[46:49], v[88:91], v[16:31]
	v_mfma_f32_32x32x16_bf16 v[16:31], v[54:57], v[92:95], v[16:31]
	v_mfma_f32_32x32x16_bf16 v[16:31], v[74:77], v[96:99], v[16:31]
	v_mfma_f32_32x32x16_bf16 v[16:31], v[108:111], v[100:103], v[16:31]
	s_and_saveexec_b64 s[2:3], vcc
	s_cbranch_execz .LBB0_169
	v_add_u32_e32 v34, 0x13000, v143
	v_mad_u64_u32 v[32:33], s[4:5], v132, 3, v[32:33]
	v_readfirstlane_b32 s4, v34
	s_mov_b32 m0, s4
	s_nop 0
	global_load_lds_dwordx4 v[32:33], off
.LBB0_169:
	s_or_b64 exec, exec, s[2:3]
	v_lshrrev_b32_e32 v33, 3, v37
	v_and_b32_e32 v34, 1, v40
	v_lshlrev_b32_e32 v32, 7, v39
	v_and_or_b32 v33, v33, 2, v34
	v_lshlrev_b32_e32 v34, 3, v36
	v_lshlrev_b32_e32 v33, 4, v33
	v_and_b32_e32 v34, 8, v34
	v_lshlrev_b32_e32 v35, 5, v39
	v_lshl_or_b32 v32, v38, 9, v32
	v_cndmask_b32_e64 v155, 3, 2, s[38:39]
	s_mov_b32 s19, 4
	v_and_b32_e32 v156, 64, v35
	v_bitop3_b32 v157, v35, 64, v35 bitop3:0xc
	v_or3_b32 v158, v32, v33, v34
	v_max_f32_e32 v32, v1, v1
	v_max_f32_e32 v33, v0, v0
	v_max_f32_e32 v32, v33, v32
	v_max3_f32 v32, v32, v2, v3
	v_max3_f32 v32, v32, v4, v5
	v_max3_f32 v32, v32, v6, v7
	v_max3_f32 v32, v32, v8, v9
	v_max3_f32 v32, v32, v10, v11
	v_max3_f32 v32, v32, v12, v13
	v_max3_f32 v32, v32, v14, v15
	v_max3_f32 v32, v32, v16, v17
	v_max3_f32 v32, v32, v18, v19
	v_max3_f32 v32, v32, v20, v21
	v_max3_f32 v32, v32, v22, v23
	v_max3_f32 v32, v32, v24, v25
	v_max3_f32 v32, v32, v26, v27
	v_max3_f32 v32, v32, v28, v29
	v_max3_f32 v32, v32, v30, v31
	v_mov_b32_e32 v33, v32
	s_nop 1
	v_permlane32_swap_b32_e32 v32, v33
	v_max_f32_e32 v33, v33, v33
	v_max_f32_e32 v32, v32, v32
	v_max_f32_e32 v78, v32, v33
	v_sub_f32_e32 v4, v4, v78
	v_exp_f32_e64 v32, -v78
	v_sub_f32_e32 v0, v0, v78
	v_sub_f32_e32 v1, v1, v78
	v_sub_f32_e32 v2, v2, v78
	v_sub_f32_e32 v3, v3, v78
	v_sub_f32_e32 v5, v5, v78
	v_sub_f32_e32 v6, v6, v78
	v_sub_f32_e32 v7, v7, v78
	v_exp_f32_e32 v107, v4
	v_add3_u32 v4, 0, v156, v158
	v_exp_f32_e32 v79, v0
	v_exp_f32_e32 v104, v1
	v_exp_f32_e32 v105, v2
	v_exp_f32_e32 v106, v3
	v_exp_f32_e32 v108, v5
	v_exp_f32_e32 v109, v6
	v_exp_f32_e32 v110, v7
	ds_read_b64_tr_b16 v[0:1], v4 offset:12288
	ds_read_b64_tr_b16 v[2:3], v4 offset:13312
	v_mul_f32_e32 v32, 0, v32
	v_sub_f32_e32 v16, v16, v78
	v_sub_f32_e32 v17, v17, v78
	v_sub_f32_e32 v18, v18, v78
	v_sub_f32_e32 v19, v19, v78
	v_sub_f32_e32 v20, v20, v78
	v_sub_f32_e32 v21, v21, v78
	v_sub_f32_e32 v22, v22, v78
	v_sub_f32_e32 v23, v23, v78
	v_sub_f32_e32 v24, v24, v78
	v_sub_f32_e32 v25, v25, v78
	v_sub_f32_e32 v26, v26, v78
	v_sub_f32_e32 v27, v27, v78
	v_sub_f32_e32 v28, v28, v78
	v_sub_f32_e32 v29, v29, v78
	v_sub_f32_e32 v30, v30, v78
	v_sub_f32_e32 v31, v31, v78
	v_cvt_pk_bf16_f32 v60, v79, v104
	v_cvt_pk_bf16_f32 v61, v105, v106
	v_cvt_pk_bf16_f32 v62, v107, v108
	v_cvt_pk_bf16_f32 v63, v109, v110
	v_mov_b32_e32 v33, v32
	v_mov_b32_e32 v34, v32
	v_mov_b32_e32 v35, v32
	v_mov_b32_e32 v36, v32
	v_mov_b32_e32 v37, v32
	v_mov_b32_e32 v38, v32
	v_mov_b32_e32 v39, v32
	v_mov_b32_e32 v40, v32
	v_mov_b32_e32 v41, v32
	v_mov_b32_e32 v42, v32
	v_mov_b32_e32 v43, v32
	v_mov_b32_e32 v44, v32
	v_mov_b32_e32 v45, v32
	v_mov_b32_e32 v46, v32
	v_mov_b32_e32 v47, v32
	v_exp_f32_e32 v119, v16
	v_exp_f32_e32 v120, v17
	v_exp_f32_e32 v121, v18
	v_exp_f32_e32 v122, v19
	v_exp_f32_e32 v123, v20
	v_exp_f32_e32 v124, v21
	v_exp_f32_e32 v125, v22
	v_exp_f32_e32 v126, v23
	v_exp_f32_e32 v127, v24
	v_exp_f32_e32 v134, v25
	v_exp_f32_e32 v135, v26
	v_exp_f32_e32 v136, v27
	v_exp_f32_e32 v137, v28
	v_exp_f32_e32 v138, v29
	v_exp_f32_e32 v139, v30
	v_exp_f32_e32 v140, v31
	s_waitcnt lgkmcnt(0)
; #define MFMA(a, b, c) __builtin_amdgcn_mfma_f32_32x32x16_bf16((a), (b), (c), 0, 0, 0)
; DEV float fast_exp2(float x) { return __builtin_amdgcn_exp2f(x); }
; template <int DQK, int DV, int NKH, int MODE>
; DEV void flash_unit(const FlashArgs& fa, char* smem, f32x16 (&oacc)[DV / 32], float& linv_out) {
;     ...
;       float psum = 0.f;
; #pragma unroll
;       for (int k2 = 0; k2 < 2; ++k2)
; #pragma unroll
;         for (int e = 0; e < 16; ++e) { st[k2][e] = fast_exp2(st[k2][e]); psum += st[k2][e]; }
;       lrun += psum;
;       bf16x8 pf[2][2];
; #pragma unroll
;       for (int k2 = 0; k2 < 2; ++k2)
; #pragma unroll
;         for (int s2 = 0; s2 < 2; ++s2) {
;           uint4 u = make_uint4(pk2(st[k2][8 * s2], st[k2][8 * s2 + 1]), pk2(st[k2][8 * s2 + 2], st[k2][8 * s2 + 3]),
;                                pk2(st[k2][8 * s2 + 4], st[k2][8 * s2 + 5]), pk2(st[k2][8 * s2 + 6], st[k2][8 * s2 + 7]));
;           pf[k2][s2] = __builtin_bit_cast(bf16x8, u);
;         }
; #pragma unroll
;       for (int v = 0; v < NV; ++v)
; #pragma unroll
;         for (int k2 = 0; k2 < 2; ++k2)
; #pragma unroll
;           for (int s2 = 0; s2 < 2; ++s2) {
;             const char* a1 = vb + (k2 * 32 + s2 * 16) * VROW + vhi[v] + vlow0;
;             const char* a2 = vb + (k2 * 32 + s2 * 16 + 8) * VROW + vhi[v] + vlow1;
;             s16x4 lo = __builtin_amdgcn_ds_read_tr16_b64_v4i16((__attribute__((address_space(3))) s16x4*)(a1));
;             s16x4 hi = __builtin_amdgcn_ds_read_tr16_b64_v4i16((__attribute__((address_space(3))) s16x4*)(a2));
;             const bf16x8 vf = __builtin_shufflevector(lo, hi, 0, 1, 2, 3, 4, 5, 6, 7);
;             oacc[v] = MFMA(vf, pf[k2][s2], oacc[v]);
;           }
	v_mfma_f32_32x32x16_bf16 v[16:31], v[0:3], v[60:63], v[32:47]
	v_sub_f32_e32 v8, v8, v78
	v_sub_f32_e32 v9, v9, v78
	v_sub_f32_e32 v10, v10, v78
	v_sub_f32_e32 v11, v11, v78
	v_sub_f32_e32 v12, v12, v78
	v_sub_f32_e32 v13, v13, v78
	v_sub_f32_e32 v14, v14, v78
	v_sub_f32_e32 v15, v15, v78
	v_exp_f32_e32 v111, v8
	v_exp_f32_e32 v112, v9
	v_exp_f32_e32 v113, v10
	v_exp_f32_e32 v114, v11
	v_exp_f32_e32 v115, v12
	v_exp_f32_e32 v116, v13
	v_exp_f32_e32 v117, v14
	v_exp_f32_e32 v118, v15
	ds_read_b64_tr_b16 v[0:1], v4 offset:14336
	ds_read_b64_tr_b16 v[2:3], v4 offset:15360
	v_cvt_pk_bf16_f32 v52, v111, v112
	v_cvt_pk_bf16_f32 v53, v113, v114
	v_cvt_pk_bf16_f32 v54, v115, v116
	v_cvt_pk_bf16_f32 v55, v117, v118
	v_cvt_pk_bf16_f32 v56, v119, v120
	v_cvt_pk_bf16_f32 v57, v121, v122
	s_waitcnt lgkmcnt(0)
	v_mfma_f32_32x32x16_bf16 v[16:31], v[0:3], v[52:55], v[16:31]
	ds_read_b64_tr_b16 v[0:1], v4 offset:16384
	ds_read_b64_tr_b16 v[2:3], v4 offset:17408
	v_cvt_pk_bf16_f32 v58, v123, v124
	v_cvt_pk_bf16_f32 v59, v125, v126
	v_cvt_pk_bf16_f32 v48, v127, v134
	v_cvt_pk_bf16_f32 v49, v135, v136
	v_cvt_pk_bf16_f32 v50, v137, v138
	v_cvt_pk_bf16_f32 v51, v139, v140
	s_waitcnt lgkmcnt(0)
	v_mfma_f32_32x32x16_bf16 v[16:31], v[0:3], v[56:59], v[16:31]
	ds_read_b64_tr_b16 v[0:1], v4 offset:18432
	ds_read_b64_tr_b16 v[2:3], v4 offset:19456
	v_add3_u32 v141, 0, v157, v158
	ds_read_b64_tr_b16 v[74:75], v141 offset:12288
	ds_read_b64_tr_b16 v[76:77], v141 offset:13312
	s_add_i32 s20, s18, -2
	s_waitcnt lgkmcnt(2)
	v_mfma_f32_32x32x16_bf16 v[16:31], v[0:3], v[48:51], v[16:31]
	v_mov_b64_e32 v[0:1], v[32:33]
	v_mov_b64_e32 v[2:3], v[34:35]
	v_mov_b64_e32 v[4:5], v[36:37]
	v_mov_b64_e32 v[6:7], v[38:39]
	v_mov_b64_e32 v[8:9], v[40:41]
	v_mov_b64_e32 v[10:11], v[42:43]
	v_mov_b64_e32 v[12:13], v[44:45]
	v_mov_b64_e32 v[14:15], v[46:47]
	v_add_f32_e32 v33, 0, v79
	v_add_f32_e32 v33, v104, v33
	v_add_f32_e32 v33, v105, v33
	v_add_f32_e32 v33, v106, v33
	s_waitcnt lgkmcnt(0)
	v_mfma_f32_32x32x16_bf16 v[0:15], v[74:77], v[60:63], v[0:15]
	v_add_f32_e32 v33, v107, v33
	v_add_f32_e32 v33, v108, v33
	v_add_f32_e32 v33, v109, v33
	ds_read_b64_tr_b16 v[34:35], v141 offset:14336
	ds_read_b64_tr_b16 v[36:37], v141 offset:15360
	v_add_f32_e32 v33, v110, v33
	v_add_f32_e32 v33, v111, v33
	v_add_f32_e32 v33, v112, v33
	v_add_f32_e32 v33, v113, v33
	v_add_f32_e32 v33, v114, v33
	s_waitcnt lgkmcnt(0)
	v_mfma_f32_32x32x16_bf16 v[0:15], v[34:37], v[52:55], v[0:15]
	v_add_f32_e32 v33, v115, v33
	v_add_f32_e32 v33, v116, v33
	v_add_f32_e32 v33, v117, v33
	ds_read_b64_tr_b16 v[34:35], v141 offset:16384
	ds_read_b64_tr_b16 v[36:37], v141 offset:17408
	v_add_f32_e32 v33, v118, v33
	v_add_f32_e32 v33, v119, v33
	v_add_f32_e32 v33, v120, v33
	v_add_f32_e32 v33, v121, v33
	v_add_f32_e32 v33, v122, v33
	s_waitcnt lgkmcnt(0)
	v_mfma_f32_32x32x16_bf16 v[0:15], v[34:37], v[56:59], v[0:15]
	v_add_f32_e32 v33, v123, v33
	v_add_f32_e32 v33, v124, v33
	v_add_f32_e32 v33, v125, v33
	ds_read_b64_tr_b16 v[34:35], v141 offset:18432
	ds_read_b64_tr_b16 v[36:37], v141 offset:19456
	v_add_f32_e32 v33, v126, v33
	v_add_f32_e32 v33, v127, v33
	v_add_f32_e32 v33, v134, v33
	v_add_f32_e32 v33, v135, v33
	v_add_f32_e32 v33, v136, v33
	s_waitcnt lgkmcnt(0)
	v_mfma_f32_32x32x16_bf16 v[0:15], v[34:37], v[48:51], v[0:15]
	v_add_f32_e32 v33, v137, v33
	v_add_f32_e32 v33, v138, v33
	v_add_f32_e32 v33, v139, v33
	v_add_f32_e32 v34, v140, v33
	v_mov_b32_e32 v33, v78
	v_mov_b32_e32 v35, v145
	v_pk_add_f32 v[134:135], v[32:33], v[34:35]
	v_lshl_add_u64 v[34:35], v[132:133], 2, v[72:73]
	v_lshl_add_u64 v[136:137], v[70:71], 0, v[34:35]
	v_lshl_add_u64 v[34:35], v[130:131], 2, v[144:145]
	v_xor_b32_e32 v32, 0x80000000, v135
	v_lshl_add_u64 v[138:139], v[68:69], 0, v[34:35]
	v_lshl_add_u64 v[34:35], v[128:129], 2, v[66:67]
	v_lshl_add_u64 v[140:141], v[64:65], 0, v[34:35]
	v_mov_b32_e32 v33, v32
	v_mov_b32_e32 v34, v32
	v_mov_b32_e32 v35, v32
	v_mov_b32_e32 v36, v32
	v_mov_b32_e32 v37, v32
	v_mov_b32_e32 v38, v32
	v_mov_b32_e32 v39, v32
	v_mov_b32_e32 v40, v32
	v_mov_b32_e32 v41, v32
	v_mov_b32_e32 v42, v32
	v_mov_b32_e32 v43, v32
	v_mov_b32_e32 v44, v32
	v_mov_b32_e32 v45, v32
	v_mov_b32_e32 v46, v32
	v_mov_b32_e32 v47, v32
	s_branch .LBB0_171

; #define MFMA(a, b, c) __builtin_amdgcn_mfma_f32_32x32x16_bf16((a), (b), (c), 0, 0, 0)
; template <int DQK, int DV, int NKH, int MODE>
; DEV void flash_unit(const FlashArgs& fa, char* smem, f32x16 (&oacc)[DV / 32], float& linv_out) {
;     ...
;     if (active) {
;       const char* sb = smem + (it & (NSTG - 1)) * STAGE;
;       const char* kb = sb + kh * 8192 + r * 128;
;       const char* kb32 = sb + OFF_K32 + r * 64;
;       const char* vb = sb + OFF_V;
;       f32x16 st[2];
;       bf16x8 kfr[2][NS];
; #pragma unroll
;       for (int k2 = 0; k2 < 2; ++k2)
; #pragma unroll
;         for (int s = 0; s < NS; ++s) {
;           if (s < 4) kfr[k2][s] = *(const bf16x8*)(kb + k2 * 32 * 128 + kxo[s]);
;           else kfr[k2][s] = *(const bf16x8*)(kb32 + k2 * 32 * 64 + (((2 * (s - 4) + h) ^ k32x) << 4));
;         }
;       __builtin_amdgcn_sched_barrier(0);
; #pragma unroll
;       for (int k2 = 0; k2 < 2; ++k2) {
; #pragma unroll
;         for (int s = 0; s < NS; ++s) {
;           const bf16x8 kf = kfr[k2][s];
;           if (s == 0) st[k2] = MFMA(kf, qf[s], negm);
;           else st[k2] = MFMA(kf, qf[s], st[k2]);
;           constexpr int NQK = 2 * NS, EVERY = NQK / LPT;
;           const int m = k2 * NS + s;
;           if ((m + 1) % EVERY == 0 && (m + 1) / EVERY <= LPT) {
;             __builtin_amdgcn_sched_barrier(0);
;             if (pre) issue_piece(it + 3, (m + 1) / EVERY - 1);
;             __builtin_amdgcn_sched_barrier(0);
;           }
;         }
;       }
.LBB0_236:
	v_lshrrev_b32_e32 v0, 1, v48
	v_bfe_u32 v1, v48, 1, 3
	v_bitop3_b32 v2, v51, v0, 7 bitop3:0x78
	v_lshlrev_b32_e32 v135, 4, v2
	v_bitop3_b32 v2, v51, v1, 2 bitop3:0x36
	v_lshlrev_b32_e32 v134, 7, v50
	v_lshlrev_b32_e32 v136, 4, v2
	v_bitop3_b32 v2, v51, v1, 4 bitop3:0x36
	v_bitop3_b32 v1, v51, v1, 6 bitop3:0x36
	v_lshlrev_b32_e32 v138, 4, v1
	v_add_u32_e32 v1, 0, v134
	v_lshlrev_b32_e32 v137, 4, v2
	v_add_u32_e32 v6, v1, v135
	s_barrier
	v_add_u32_e32 v7, v1, v136
	v_add_u32_e32 v8, v1, v137
	v_add_u32_e32 v1, v1, v138
	ds_read_b128 v[2:5], v6
	ds_read_b128 v[18:21], v6 offset:4096
	ds_read_b128 v[22:25], v7
	ds_read_b128 v[34:37], v7 offset:4096
	ds_read_b128 v[26:29], v8
	ds_read_b128 v[38:41], v8 offset:4096
	ds_read_b128 v[30:33], v1
	ds_read_b128 v[42:45], v1 offset:4096
	s_cmp_gt_u32 s37, 3
	s_cselect_b64 s[0:1], -1, 0
	s_cmp_lt_u32 s37, 4
	s_waitcnt lgkmcnt(0)
	v_mfma_f32_32x32x16_bf16 v[2:17], v[2:5], v[88:91], 0
	v_mfma_f32_32x32x16_bf16 v[2:17], v[22:25], v[80:83], v[2:17]
	v_mfma_f32_32x32x16_bf16 v[2:17], v[26:29], v[84:87], v[2:17]
	v_mfma_f32_32x32x16_bf16 v[2:17], v[30:33], v[92:95], v[2:17]
	s_cbranch_scc1 .LBB0_238
	s_mov_b64 s[2:3], 0x6000
	v_add_u32_e32 v1, 0xc000, v133
	v_lshl_add_u64 v[22:23], v[114:115], 0, s[2:3]
	v_readfirstlane_b32 s2, v1
	s_mov_b32 m0, s2
	s_nop 0
	global_load_lds_dwordx4 v[22:23], off

; template <int DQK, int DV, int NKH, int MODE>
; DEV void flash_unit(const FlashArgs& fa, char* smem, f32x16 (&oacc)[DV / 32], float& linv_out) {
;     ...
;       float rel = st[0][0];
; #pragma unroll
;       for (int e = 1; e < 16; ++e) rel = fmaxf(rel, st[0][e]);
; #pragma unroll
;       for (int e = 0; e < 16; ++e) rel = fmaxf(rel, st[1][e]);
;       rel = half_max(rel);
;       const bool first = (it == 0);
;       if (first || __builtin_amdgcn_ballot_w64(rel > 8.f) != 0) {
;         const float d = first ? rel : fmaxf(rel, 0.f);
;         const float alpha = fast_exp2(-d);
;         mrun += d;
; #pragma unroll
;         for (int k2 = 0; k2 < 2; ++k2)
; #pragma unroll
;           for (int e = 0; e < 16; ++e) st[k2][e] -= d;
; #pragma unroll
;         for (int v = 0; v < NV; ++v)
; #pragma unroll
;           for (int e = 0; e < 16; ++e) oacc[v][e] *= alpha;
; #pragma unroll
;         for (int e = 0; e < 16; ++e) negm[e] = -mrun;
;         lrun *= alpha;
;       }
;       float psum = 0.f;
; #pragma unroll
;       for (int k2 = 0; k2 < 2; ++k2)
; #pragma unroll
;         for (int e = 0; e < 16; ++e) { st[k2][e] = fast_exp2(st[k2][e]); psum += st[k2][e]; }
;       lrun += psum;
;       bf16x8 pf[2][2];
; #pragma unroll
;       for (int k2 = 0; k2 < 2; ++k2)
; #pragma unroll
;         for (int s2 = 0; s2 < 2; ++s2) {
;           uint4 u = make_uint4(pk2(st[k2][8 * s2], st[k2][8 * s2 + 1]), pk2(st[k2][8 * s2 + 2], st[k2][8 * s2 + 3]),
;                                pk2(st[k2][8 * s2 + 4], st[k2][8 * s2 + 5]), pk2(st[k2][8 * s2 + 6], st[k2][8 * s2 + 7]));
;           pf[k2][s2] = __builtin_bit_cast(bf16x8, u);
;         }
; #pragma unroll
;       for (int v = 0; v < NV; ++v)
; #pragma unroll
;         for (int k2 = 0; k2 < 2; ++k2)
; #pragma unroll
;           for (int s2 = 0; s2 < 2; ++s2) {
;             const char* a1 = vb + (k2 * 32 + s2 * 16) * VROW + vhi[v] + vlow0;
;             const char* a2 = vb + (k2 * 32 + s2 * 16 + 8) * VROW + vhi[v] + vlow1;
;             s16x4 lo = __builtin_amdgcn_ds_read_tr16_b64_v4i16((__attribute__((address_space(3))) s16x4*)(a1));
;             s16x4 hi = __builtin_amdgcn_ds_read_tr16_b64_v4i16((__attribute__((address_space(3))) s16x4*)(a2));
;             const bf16x8 vf = __builtin_shufflevector(lo, hi, 0, 1, 2, 3, 4, 5, 6, 7);
;             oacc[v] = MFMA(vf, pf[k2][s2], oacc[v]);
;           }
.LBB0_240:
	v_lshlrev_b32_e32 v1, 5, v48
	v_lshrrev_b32_e32 v34, 3, v48
	v_and_b32_e32 v0, 1, v0
	v_and_b32_e32 v1, 0x180, v1
	v_and_or_b32 v0, v34, 2, v0
	v_lshlrev_b32_e32 v34, 3, v46
	v_lshlrev_b32_e32 v0, 4, v0
	v_and_b32_e32 v34, 8, v34
	v_lshlrev_b32_e32 v35, 3, v48
	v_lshl_or_b32 v1, v51, 9, v1
	v_and_b32_e32 v139, 64, v35
	v_bitop3_b32 v140, v35, 64, v35 bitop3:0xc
	v_or3_b32 v141, v1, v0, v34
	v_max_f32_e32 v0, v3, v3
	v_max_f32_e32 v1, v2, v2
	v_max_f32_e32 v0, v1, v0
	v_max3_f32 v0, v0, v4, v5
	v_max3_f32 v0, v0, v6, v7
	v_max3_f32 v0, v0, v8, v9
	v_max3_f32 v0, v0, v10, v11
	v_max3_f32 v0, v0, v12, v13
	v_max3_f32 v0, v0, v14, v15
	v_max3_f32 v0, v0, v16, v17
	v_max3_f32 v0, v0, v18, v19
	v_max3_f32 v0, v0, v20, v21
	v_max3_f32 v0, v0, v22, v23
	v_max3_f32 v0, v0, v24, v25
	v_max3_f32 v0, v0, v26, v27
	v_max3_f32 v0, v0, v28, v29
	v_max3_f32 v0, v0, v30, v31
	v_max3_f32 v0, v0, v32, v33
	v_mov_b32_e32 v1, v0
	s_nop 1
	v_permlane32_swap_b32_e32 v0, v1
	v_max_f32_e32 v1, v1, v1
	v_max_f32_e32 v0, v0, v0
	v_max_f32_e32 v49, v0, v1
	v_sub_f32_e32 v1, v2, v49
	v_sub_f32_e32 v2, v3, v49
	v_exp_f32_e32 v1, v1
	v_sub_f32_e32 v3, v4, v49
	v_exp_f32_e32 v2, v2
	v_sub_f32_e32 v4, v5, v49
	v_exp_f32_e32 v3, v3
	v_sub_f32_e32 v5, v6, v49
	v_exp_f32_e32 v4, v4
	v_sub_f32_e32 v6, v7, v49
	v_sub_f32_e32 v7, v8, v49
	v_sub_f32_e32 v8, v9, v49
	v_sub_f32_e32 v9, v10, v49
	v_sub_f32_e32 v10, v11, v49
	v_sub_f32_e32 v11, v12, v49
	v_sub_f32_e32 v12, v13, v49
	v_sub_f32_e32 v13, v14, v49
	v_sub_f32_e32 v14, v15, v49
	v_sub_f32_e32 v15, v16, v49
	v_sub_f32_e32 v16, v17, v49
	v_sub_f32_e32 v17, v18, v49
	v_sub_f32_e32 v18, v19, v49
	v_sub_f32_e32 v19, v20, v49
	v_sub_f32_e32 v20, v21, v49
	v_sub_f32_e32 v21, v22, v49
	v_sub_f32_e32 v22, v23, v49
	v_sub_f32_e32 v23, v24, v49
	v_sub_f32_e32 v24, v25, v49
	v_sub_f32_e32 v25, v26, v49
	v_sub_f32_e32 v26, v27, v49
	v_sub_f32_e32 v27, v28, v49
	v_sub_f32_e32 v28, v29, v49
	v_sub_f32_e32 v29, v30, v49
	v_sub_f32_e32 v30, v31, v49
	v_sub_f32_e32 v31, v32, v49
	v_sub_f32_e32 v32, v33, v49
	v_add_f32_e32 v33, 0, v1
	v_exp_f32_e32 v5, v5
	v_add_f32_e32 v33, v2, v33
	v_exp_f32_e32 v6, v6
	v_add_f32_e32 v33, v3, v33
	v_exp_f32_e32 v7, v7
	v_add_f32_e32 v33, v4, v33
	v_exp_f32_e32 v8, v8
	v_add_f32_e32 v33, v5, v33
	v_exp_f32_e32 v9, v9
	v_add_f32_e32 v33, v6, v33
	v_exp_f32_e32 v10, v10
	v_add_f32_e32 v33, v7, v33
	v_exp_f32_e32 v11, v11
	v_add_f32_e32 v33, v8, v33
	v_exp_f32_e32 v12, v12
	v_add_f32_e32 v33, v9, v33
	v_exp_f32_e32 v13, v13
	v_add_f32_e32 v33, v10, v33
	v_exp_f32_e32 v14, v14
	v_add_f32_e32 v33, v11, v33
	v_exp_f32_e32 v15, v15
	v_add_f32_e32 v33, v12, v33
	v_exp_f32_e32 v16, v16
	v_add_f32_e32 v33, v13, v33
	v_exp_f32_e32 v17, v17
	v_add_f32_e32 v33, v14, v33
	v_exp_f32_e32 v18, v18
	v_add_f32_e32 v33, v15, v33
	v_exp_f32_e32 v19, v19
	v_add_f32_e32 v33, v16, v33
	v_exp_f32_e32 v20, v20
	v_add_f32_e32 v33, v17, v33
	v_exp_f32_e32 v21, v21
	v_add_f32_e32 v33, v18, v33
	v_exp_f32_e32 v22, v22
	v_add_f32_e32 v33, v19, v33
	v_exp_f32_e32 v23, v23
	v_add_f32_e32 v33, v20, v33
	v_exp_f32_e32 v24, v24
	v_add_f32_e32 v33, v21, v33
	v_exp_f32_e32 v25, v25
	v_add_f32_e32 v33, v22, v33
	v_exp_f32_e32 v26, v26
	v_add_f32_e32 v33, v23, v33
	v_exp_f32_e32 v27, v27
	v_add_f32_e32 v33, v24, v33
	v_exp_f32_e32 v28, v28
	v_add_f32_e32 v33, v25, v33
	v_exp_f32_e32 v29, v29
	v_exp_f32_e64 v53, -v49
	v_add_f32_e32 v33, v26, v33
	v_exp_f32_e32 v30, v30
	v_add3_u32 v58, 0, v139, v141
	v_add_f32_e32 v33, v27, v33
	v_exp_f32_e32 v31, v31
	ds_read_b64_tr_b16 v[54:55], v58 offset:8192
	ds_read_b64_tr_b16 v[56:57], v58 offset:9216
	v_add_f32_e32 v33, v28, v33
	v_exp_f32_e32 v35, v32
	v_add_f32_e32 v33, v29, v33
	v_mul_f32_e32 v0, 0, v53
	v_add_f32_e32 v33, v30, v33
	v_add_f32_e32 v33, v31, v33
	v_cvt_pk_bf16_f32 v44, v1, v2
	v_cvt_pk_bf16_f32 v45, v3, v4
	v_cvt_pk_bf16_f32 v46, v5, v6
	v_cvt_pk_bf16_f32 v47, v7, v8
	v_cvt_pk_bf16_f32 v40, v9, v10
	v_cvt_pk_bf16_f32 v41, v11, v12
	v_cvt_pk_bf16_f32 v42, v13, v14
	v_cvt_pk_bf16_f32 v43, v15, v16
	v_mov_b32_e32 v1, v0
	v_mov_b32_e32 v2, v0
	v_mov_b32_e32 v3, v0
	v_mov_b32_e32 v4, v0
	v_mov_b32_e32 v5, v0
	v_mov_b32_e32 v6, v0
	v_mov_b32_e32 v7, v0
	v_mov_b32_e32 v8, v0
	v_mov_b32_e32 v9, v0
	v_mov_b32_e32 v10, v0
	v_mov_b32_e32 v11, v0
	v_mov_b32_e32 v12, v0
	v_mov_b32_e32 v13, v0
	v_mov_b32_e32 v14, v0
	v_mov_b32_e32 v15, v0
	v_add_f32_e32 v142, v35, v33
	v_cvt_pk_bf16_f32 v36, v17, v18
	v_cvt_pk_bf16_f32 v37, v19, v20
	v_cvt_pk_bf16_f32 v38, v21, v22
	v_cvt_pk_bf16_f32 v39, v23, v24
	v_cvt_pk_bf16_f32 v32, v25, v26
	v_cvt_pk_bf16_f32 v33, v27, v28
	v_cvt_pk_bf16_f32 v34, v29, v30
	v_cvt_pk_bf16_f32 v35, v31, v35
	s_waitcnt lgkmcnt(0)
	v_mfma_f32_32x32x16_bf16 v[16:31], v[54:57], v[44:47], v[0:15]
	ds_read_b64_tr_b16 v[54:55], v58 offset:10240
	ds_read_b64_tr_b16 v[56:57], v58 offset:11264
	v_fmac_f32_e32 v142, 0, v53
	s_cmp_eq_u32 s37, 1
	s_waitcnt lgkmcnt(0)
	v_mfma_f32_32x32x16_bf16 v[16:31], v[54:57], v[40:43], v[16:31]
	ds_read_b64_tr_b16 v[54:55], v58 offset:12288
	ds_read_b64_tr_b16 v[56:57], v58 offset:13312
	s_waitcnt lgkmcnt(0)
	v_mfma_f32_32x32x16_bf16 v[16:31], v[54:57], v[36:39], v[16:31]
	ds_read_b64_tr_b16 v[54:55], v58 offset:14336
	ds_read_b64_tr_b16 v[56:57], v58 offset:15360
	v_add3_u32 v58, 0, v140, v141
	s_waitcnt lgkmcnt(0)
	v_mfma_f32_32x32x16_bf16 v[16:31], v[54:57], v[32:35], v[16:31]
	ds_read_b64_tr_b16 v[54:55], v58 offset:8192
	ds_read_b64_tr_b16 v[56:57], v58 offset:9216
	s_waitcnt lgkmcnt(0)
	v_mfma_f32_32x32x16_bf16 v[0:15], v[54:57], v[44:47], v[0:15]
	ds_read_b64_tr_b16 v[44:45], v58 offset:10240
	ds_read_b64_tr_b16 v[46:47], v58 offset:11264
	s_waitcnt lgkmcnt(0)
	v_mfma_f32_32x32x16_bf16 v[0:15], v[44:47], v[40:43], v[0:15]
	ds_read_b64_tr_b16 v[40:41], v58 offset:12288
	ds_read_b64_tr_b16 v[42:43], v58 offset:13312
	s_waitcnt lgkmcnt(0)
	v_mfma_f32_32x32x16_bf16 v[0:15], v[40:43], v[36:39], v[0:15]
	ds_read_b64_tr_b16 v[36:37], v58 offset:14336
	ds_read_b64_tr_b16 v[38:39], v58 offset:15360
	s_waitcnt lgkmcnt(0)
	v_mfma_f32_32x32x16_bf16 v[0:15], v[36:39], v[32:35], v[0:15]
	s_cbranch_scc1 .LBB0_202
; DEV int crow_of(int reg, int h) { return (reg & 3) + 8 * (reg >> 2) + 4 * h; }
; template <int DQK, int DV, int NKH, int MODE>
; DEV void flash_unit(const FlashArgs& fa, char* smem, f32x16 (&oacc)[DV / 32], float& linv_out) {
;     ...
;   int na_row = 0, na_rs = 0, na_qc = 0, na_cstart = 0;
;   if (MODE == 1) {
;     na_row = fa.r0 + (w >> 1);
;     na_rs = min(max(na_row - 4, 0), 120);
;     na_qc = (w & 1) * 32 + r;
;     na_cstart = min(max(na_qc - 8, 0), 48);
;     ...
;       if (MODE == 1 && it >= 4) {
;         const int dr = krow - na_row + 7;
;         const float* bp = rpbs + dr * 31;
; #pragma unroll
;         for (int k2 = 0; k2 < 2; ++k2)
; #pragma unroll
;           for (int e = 0; e < 16; ++e) {
;             const int kc = k2 * 32 + crow_of(e, h);
;             const bool valid = (kc >= na_cstart) && (kc < na_cstart + 16);
;             const int idx = min(max(kc - na_qc + 15, 0), 30);
;             const float bv = bp[idx];
;             st[k2][e] = valid ? st[k2][e] + bv : -1e30f;
;           }
	v_ashrrev_i32_e32 v32, 7, v48
	v_add_u32_e32 v33, s8, v32
	v_max_i32_e32 v32, 4, v33
	v_add_u32_e32 v32, -4, v32
	v_and_b32_e32 v34, 32, v52
	v_min_u32_e32 v143, 0x78, v32
	v_or_b32_e32 v32, v34, v50
	v_sub_u32_e64 v32, v32, 8 clamp
	v_lshlrev_b32_e32 v35, 2, v51
	v_min_u32_e32 v32, 48, v32
	v_or_b32_e32 v37, 1, v35
	v_cmp_ge_u32_e64 s[40:41], v37, v32
	v_or_b32_e32 v37, 2, v35
	v_cmp_ge_u32_e64 s[42:43], v37, v32
	v_or_b32_e32 v37, 3, v35
	v_cmp_ge_u32_e64 s[44:45], v37, v32
	v_or_b32_e32 v37, 8, v35
	v_cmp_ge_u32_e64 s[46:47], v37, v32
	v_or_b32_e32 v37, 9, v35
	s_mov_b32 s34, s48
	v_cmp_ge_u32_e64 s[48:49], v37, v32
	v_or_b32_e32 v37, 10, v35
	v_cmp_ge_u32_e64 s[50:51], v37, v32
	v_or_b32_e32 v37, 11, v35
	v_cmp_ge_u32_e64 s[52:53], v37, v32
	v_or_b32_e32 v37, 16, v35
	v_add_u32_e32 v36, 16, v32
	v_cmp_lt_u32_e32 vcc, v35, v32
	v_cmp_ge_u32_e64 s[0:1], v37, v32
	v_or_b32_e32 v37, 17, v35
	s_and_b64 s[86:87], s[0:1], vcc
	v_cmp_ge_u32_e32 vcc, v37, v32
	v_cmp_lt_u32_e64 s[0:1], v37, v36
	v_or_b32_e32 v37, 18, v35
	s_and_b64 s[88:89], vcc, s[0:1]
	v_cmp_ge_u32_e32 vcc, v37, v32
	v_cmp_lt_u32_e64 s[0:1], v37, v36
	v_or_b32_e32 v37, 19, v35
	s_and_b64 s[90:91], vcc, s[0:1]
	v_cmp_ge_u32_e32 vcc, v37, v32
	v_cmp_lt_u32_e64 s[0:1], v37, v36
	v_or_b32_e32 v37, 24, v35
	s_and_b64 s[4:5], vcc, s[0:1]
	v_cmp_ge_u32_e32 vcc, v37, v32
	v_cmp_lt_u32_e64 s[0:1], v37, v36
	v_or_b32_e32 v37, 25, v35
	s_and_b64 s[6:7], vcc, s[0:1]
	v_cmp_ge_u32_e32 vcc, v37, v32
	v_cmp_lt_u32_e64 s[0:1], v37, v36
	v_or_b32_e32 v37, 26, v35
	s_and_b64 s[8:9], vcc, s[0:1]
	v_cmp_ge_u32_e32 vcc, v37, v32
	v_cmp_lt_u32_e64 s[0:1], v37, v36
	v_or_b32_e32 v37, 27, v35
	s_and_b64 s[10:11], vcc, s[0:1]
	v_cmp_ge_u32_e32 vcc, v37, v32
	v_cmp_lt_u32_e64 s[0:1], v37, v36
	v_or_b32_e32 v37, 32, v35
	s_and_b64 s[12:13], vcc, s[0:1]
	v_cmp_ge_u32_e32 vcc, v37, v32
	v_cmp_lt_u32_e64 s[0:1], v37, v36
	v_or_b32_e32 v37, 33, v35
	s_and_b64 s[14:15], vcc, s[0:1]
	v_cmp_ge_u32_e32 vcc, v37, v32
	v_cmp_lt_u32_e64 s[0:1], v37, v36
	v_or_b32_e32 v37, 34, v35
	s_and_b64 s[16:17], vcc, s[0:1]
	v_cmp_ge_u32_e32 vcc, v37, v32
	v_cmp_lt_u32_e64 s[0:1], v37, v36
	v_or_b32_e32 v37, 35, v35
	s_and_b64 s[18:19], vcc, s[0:1]
	v_cmp_ge_u32_e32 vcc, v37, v32
	v_cmp_lt_u32_e64 s[0:1], v37, v36
	v_or_b32_e32 v37, 40, v35
	s_and_b64 s[20:21], vcc, s[0:1]
	v_cmp_ge_u32_e32 vcc, v37, v32
	v_cmp_lt_u32_e64 s[0:1], v37, v36
	v_or_b32_e32 v37, 41, v35
	s_and_b64 s[22:23], vcc, s[0:1]
	v_cmp_ge_u32_e32 vcc, v37, v32
	v_cmp_lt_u32_e64 s[0:1], v37, v36
	v_or_b32_e32 v37, 42, v35
	s_and_b64 s[24:25], vcc, s[0:1]
	v_cmp_ge_u32_e32 vcc, v37, v32
	v_cmp_lt_u32_e64 s[0:1], v37, v36
	v_or_b32_e32 v37, 43, v35
	v_cmp_ge_u32_e64 s[38:39], v35, v32
	s_and_b64 s[26:27], vcc, s[0:1]
	v_cmp_ge_u32_e32 vcc, v37, v32
	v_or_b32_e32 v32, 48, v35
	v_cmp_lt_u32_e64 s[54:55], v32, v36
	v_or_b32_e32 v32, 49, v35
	v_cmp_lt_u32_e64 s[56:57], v32, v36
	v_or_b32_e32 v32, 50, v35
	v_cmp_lt_u32_e64 s[58:59], v32, v36
	v_or_b32_e32 v32, 51, v35
	v_cmp_lt_u32_e64 s[60:61], v32, v36
	v_or_b32_e32 v32, 56, v35
	v_cmp_lt_u32_e64 s[0:1], v37, v36
	v_cmp_lt_u32_e64 s[62:63], v32, v36
	v_or_b32_e32 v32, 57, v35
	s_and_b64 s[72:73], vcc, s[0:1]
	v_cmp_lt_u32_e64 s[64:65], v32, v36
	v_or_b32_e32 v32, 58, v35
	s_movk_i32 s1, 0x7c
	v_cmp_lt_u32_e64 s[66:67], v32, v36
	v_or_b32_e32 v32, 59, v35
	v_sub_u32_e32 v35, v35, v50
	s_mul_i32 s0, s36, 0x7c
	v_mul_lo_u32 v33, v33, s1
	v_sub_u32_e32 v34, v35, v34
	v_sub_u32_e32 v33, s0, v33
	v_add_u32_e32 v149, 0, v33
	v_add_u32_e32 v33, 0x49, v34
	v_min_u32_e32 v33, 30, v33
	v_lshl_or_b32 v150, v33, 2, v177
	v_add_u32_e32 v33, 0x48, v34
	v_min_u32_e32 v33, 30, v33
	v_lshl_or_b32 v151, v33, 2, v177
	v_add_u32_e32 v33, 0x47, v34
	v_min_u32_e32 v33, 30, v33
	v_lshl_or_b32 v152, v33, 2, v177
	v_add_u32_e32 v33, 0x42, v34
	v_min_u32_e32 v33, 30, v33
	v_lshl_or_b32 v153, v33, 2, v177
	v_add_u32_e32 v33, 0x41, v34
	v_min_u32_e32 v33, 30, v33
; DEV float fast_exp2(float x) { return __builtin_amdgcn_exp2f(x); }
; DEV int crow_of(int reg, int h) { return (reg & 3) + 8 * (reg >> 2) + 4 * h; }
; template <int DQK, int DV, int NKH, int MODE>
; DEV void flash_unit(const FlashArgs& fa, char* smem, f32x16 (&oacc)[DV / 32], float& linv_out) {
;     ...
;       if (MODE == 1 && it >= 4) {
;         const int dr = krow - na_row + 7;
;         const float* bp = rpbs + dr * 31;
; #pragma unroll
;         for (int k2 = 0; k2 < 2; ++k2)
; #pragma unroll
;           for (int e = 0; e < 16; ++e) {
;             const int kc = k2 * 32 + crow_of(e, h);
;             const bool valid = (kc >= na_cstart) && (kc < na_cstart + 16);
;             const int idx = min(max(kc - na_qc + 15, 0), 30);
;             const float bv = bp[idx];
;             st[k2][e] = valid ? st[k2][e] + bv : -1e30f;
;           }
;     ...
;         const float alpha = fast_exp2(-d);
;         mrun += d;
; #pragma unroll
;         for (int k2 = 0; k2 < 2; ++k2)
; #pragma unroll
;           for (int e = 0; e < 16; ++e) st[k2][e] -= d;
; #pragma unroll
;         for (int v = 0; v < NV; ++v)
; #pragma unroll
;           for (int e = 0; e < 16; ++e) oacc[v][e] *= alpha;
; #pragma unroll
;         for (int e = 0; e < 16; ++e) negm[e] = -mrun;
	v_lshl_or_b32 v154, v33, 2, v177
	v_add_u32_e32 v33, 64, v34
	v_min_u32_e32 v33, 30, v33
	v_lshl_or_b32 v155, v33, 2, v177
	v_add_u32_e32 v33, 63, v34
	v_min_u32_e32 v33, 30, v33
	v_lshl_or_b32 v156, v33, 2, v177
	v_add_u32_e32 v33, 43, v34
	v_max_i32_e32 v33, -15, v33
	v_add_u32_e32 v33, 15, v33
	v_min_u32_e32 v33, 30, v33
	v_lshl_or_b32 v157, v33, 2, v177
	v_add_u32_e32 v33, 42, v34
	v_max_i32_e32 v33, -15, v33
	v_add_u32_e32 v33, 15, v33
	v_min_u32_e32 v33, 30, v33
	v_lshl_or_b32 v158, v33, 2, v177
	v_add_u32_e32 v33, 41, v34
	v_max_i32_e32 v33, -15, v33
	v_add_u32_e32 v33, 15, v33
	v_min_u32_e32 v33, 30, v33
	v_lshl_or_b32 v159, v33, 2, v177
	v_add_u32_e32 v33, 40, v34
	v_max_i32_e32 v33, -15, v33
	v_add_u32_e32 v33, 15, v33
	v_min_u32_e32 v33, 30, v33
	v_lshl_or_b32 v160, v33, 2, v177
	v_add_u32_e32 v33, 35, v34
	v_max_i32_e32 v33, -15, v33
	v_add_u32_e32 v33, 15, v33
	v_min_u32_e32 v33, 30, v33
	v_lshl_or_b32 v161, v33, 2, v177
	v_add_u32_e32 v33, 34, v34
	v_max_i32_e32 v33, -15, v33
	v_add_u32_e32 v33, 15, v33
	v_min_u32_e32 v33, 30, v33
	v_lshl_or_b32 v162, v33, 2, v177
	v_add_u32_e32 v33, 33, v34
	v_max_i32_e32 v33, -15, v33
	v_add_u32_e32 v33, 15, v33
	v_min_u32_e32 v33, 30, v33
	v_lshl_or_b32 v163, v33, 2, v177
	v_add_u32_e32 v33, 32, v34
	v_max_i32_e32 v33, -15, v33
	v_add_u32_e32 v33, 15, v33
	v_min_u32_e32 v33, 30, v33
	v_lshl_or_b32 v164, v33, 2, v177
	v_add_u32_e32 v33, 27, v34
	v_max_i32_e32 v33, -15, v33
	v_add_u32_e32 v33, 15, v33
	v_min_u32_e32 v33, 30, v33
	v_lshl_or_b32 v165, v33, 2, v177
	v_add_u32_e32 v33, 26, v34
	v_max_i32_e32 v33, -15, v33
	v_add_u32_e32 v33, 15, v33
	v_min_u32_e32 v33, 30, v33
	v_lshl_or_b32 v181, v33, 2, v177
	v_add_u32_e32 v33, 25, v34
	v_max_i32_e32 v33, -15, v33
	v_add_u32_e32 v33, 15, v33
	v_min_u32_e32 v33, 30, v33
	v_lshl_or_b32 v182, v33, 2, v177
	v_add_u32_e32 v33, 24, v34
	v_max_i32_e32 v33, -15, v33
	v_add_u32_e32 v33, 15, v33
	v_min_u32_e32 v33, 30, v33
	v_lshl_or_b32 v183, v33, 2, v177
	v_add_u32_e32 v33, 19, v34
	v_max_i32_e32 v33, -15, v33
	v_add_u32_e32 v33, 15, v33
	v_min_u32_e32 v33, 30, v33
	v_lshl_or_b32 v184, v33, 2, v177
	v_add_u32_e32 v33, 18, v34
	v_max_i32_e32 v33, -15, v33
	v_add_u32_e32 v33, 15, v33
	v_min_u32_e32 v33, 30, v33
	v_lshl_or_b32 v185, v33, 2, v177
	v_add_u32_e32 v33, 17, v34
	v_max_i32_e32 v33, -15, v33
	v_add_u32_e32 v33, 15, v33
	v_min_u32_e32 v33, 30, v33
	v_lshl_or_b32 v186, v33, 2, v177
	v_add_u32_e32 v33, 16, v34
	v_max_i32_e32 v33, -15, v33
	v_add_u32_e32 v33, 15, v33
	v_min_u32_e32 v33, 30, v33
	v_lshl_or_b32 v187, v33, 2, v177
	v_add_u32_e32 v33, 11, v34
	v_max_i32_e32 v33, -15, v33
	v_lshl_add_u32 v188, v33, 2, v178
	v_add_u32_e32 v33, 10, v34
	v_max_i32_e32 v33, -15, v33
	v_lshl_add_u32 v189, v33, 2, v178
	v_add_u32_e32 v33, 9, v34
	v_max_i32_e32 v33, -15, v33
	v_lshl_add_u32 v190, v33, 2, v178
	v_add_u32_e32 v33, 8, v34
	v_max_i32_e32 v33, -15, v33
	v_lshl_add_u32 v191, v33, 2, v178
	v_add_u32_e32 v33, 3, v34
	v_max_i32_e32 v33, -15, v33
	v_lshl_add_u32 v192, v33, 2, v178
	v_add_u32_e32 v33, 2, v34
	v_max_i32_e32 v33, -15, v33
	v_lshl_add_u32 v193, v33, 2, v178
	v_add_u32_e32 v33, 1, v34
	v_add_f32_e32 v146, 0, v49
	v_add_u32_e32 v35, 0x4a, v34
	v_max_i32_e32 v33, -15, v33
	v_cmp_lt_u32_e64 s[68:69], v32, v36
	v_xor_b32_e32 v32, 0x80000000, v146
	v_min_u32_e32 v35, 30, v35
	v_lshl_add_u32 v194, v33, 2, v178
	v_max_i32_e32 v33, -15, v34
	s_mov_b32 s70, 4
	v_add_u32_e32 v144, 8, v143
	s_sub_i32 s71, 0, s37
	s_mov_b32 s96, 0x10000
	v_lshl_or_b32 v148, v35, 2, v177
	v_lshl_add_u32 v195, v33, 2, v178
	s_add_i32 s97, s37, -2
	v_mov_b32_e32 v33, v32
	v_mov_b32_e32 v34, v32
	v_mov_b32_e32 v35, v32
	v_mov_b32_e32 v36, v32
	v_mov_b32_e32 v37, v32
	v_mov_b32_e32 v38, v32
	v_mov_b32_e32 v39, v32
	v_mov_b32_e32 v40, v32
	v_mov_b32_e32 v41, v32
	v_mov_b32_e32 v42, v32
	v_mov_b32_e32 v43, v32
	v_mov_b32_e32 v44, v32
	v_mov_b32_e32 v45, v32
	v_mov_b32_e32 v46, v32
	v_mov_b32_e32 v47, v32
	s_branch .LBB0_244

; DEV float fast_exp2(float x) { return __builtin_amdgcn_exp2f(x); }
; DEV float xor32(float v) { return __shfl_xor(v, 32, 64); }
; DEV int crow_of(int reg, int h) { return (reg & 3) + 8 * (reg >> 2) + 4 * h; }
; DEV void phase_upproj(const Params& p, int l, int hf, char* smem) {
;     ...
;       const float rckv = rsqrtf((sqv[0] + sqv[1] + sqv[2] + sqv[3]) * (1.f / 256.f) + EPS);
;       float ss = 0;
; #pragma unroll
;       for (int i = 0; i < 4; ++i)
; #pragma unroll
;         for (int e = 0; e < 16; ++e) { acc[i][0][e] *= rckv; if (i < 2) ss += acc[i][0][e] * acc[i][0][e]; }
; #pragma unroll
;       for (int e = 0; e < 16; ++e) ss += kr[e] * kr[e];
;       ss += xor32(ss);
;       const float rs = rsqrtf(ss * (1.f / 96.f) + EPS);
;       const float* gain = p.mla_k_g + l * 96;
;       u16* krow = (u16*)(ws + OFF_MK) + ((size_t)(bl * 8 + hd) * TP + tp) * 96;
;       u16* vrow = (u16*)(ws + OFF_MV) + ((size_t)(bl * 8 + hd) * TP + tp) * 64;
; #pragma unroll
;       for (int e = 0; e < 16; ++e) kr[e] *= rs * gain[64 + crow_of(e, h)];
;       if (latent) {
; #pragma unroll
;         for (int e = 0; e < 8; ++e) {
;           const int a = crow_of(e, h);
;           const float inv = fast_exp2(-(float)(a & 7) * 1.6609640474436813f);
;           const float ang = ((a < 8) ? prow : pcol) * inv;
;           float sn, cs;
;           sincos_fast(ang, sn, cs);
;           const float x1 = kr[e], x2 = kr[e + 8];
;           kr[e] = x1 * cs - x2 * sn;
;           kr[e + 8] = x2 * cs + x1 * sn;
;         }
;       }
; #pragma unroll
;       for (int i = 0; i < 2; ++i) {
;         float ov[16];
; #pragma unroll
;         for (int g4 = 0; g4 < 4; ++g4) {
;           const int f = 32 * i + 8 * g4 + 4 * h;
;           const float4 gg = *(const float4*)(gain + f);
;           ov[4 * g4] = acc[i][0][4 * g4] * rs * gg.x; ov[4 * g4 + 1] = acc[i][0][4 * g4 + 1] * rs * gg.y;
;           ov[4 * g4 + 2] = acc[i][0][4 * g4 + 2] * rs * gg.z; ov[4 * g4 + 3] = acc[i][0][4 * g4 + 3] * rs * gg.w;
;         }
;         store_row32(krow + 32 * i, ov, h);
;       }
;       store_row32(krow + 64, kr, h);
; #pragma unroll
;       for (int i = 2; i < 4; ++i) {
;         float ov[16];
; #pragma unroll
;         for (int e = 0; e < 16; ++e) ov[e] = acc[i][0][e];
;         store_row32(vrow + 32 * (i - 2), ov, h);
;       }
.LBB0_339:
	s_or_b64 exec, exec, s[2:3]
	global_load_dwordx4 v[130:133], v[100:101], off
	global_load_dwordx4 v[216:219], v[100:101], off offset:32
	global_load_dwordx4 v[220:223], v[100:101], off offset:64
	global_load_dwordx4 v[224:227], v[100:101], off offset:96
	global_load_dwordx4 v[228:231], v[100:101], off offset:128
	global_load_dwordx4 v[232:235], v[100:101], off offset:160
	global_load_dwordx4 v[236:239], v[100:101], off offset:192
	global_load_dwordx4 v[244:247], v[100:101], off offset:224
	v_mov_b32_e32 v115, v114
	v_lshl_add_u32 v33, v151, 3, s14
	v_ashrrev_i32_e32 v111, 31, v110
	v_pk_mul_f32 v[16:17], v[114:115], v[16:17]
	v_pk_mul_f32 v[18:19], v[114:115], v[18:19]
	v_pk_mul_f32 v[20:21], v[114:115], v[20:21]
	v_pk_mul_f32 v[22:23], v[114:115], v[22:23]
	v_pk_mul_f32 v[24:25], v[114:115], v[24:25]
	v_pk_mul_f32 v[26:27], v[114:115], v[26:27]
	v_pk_mul_f32 v[28:29], v[114:115], v[28:29]
	v_pk_mul_f32 v[30:31], v[114:115], v[30:31]
	v_pk_mul_f32 v[0:1], v[114:115], v[0:1]
	v_pk_mul_f32 v[2:3], v[114:115], v[2:3]
	v_pk_mul_f32 v[4:5], v[114:115], v[4:5]
	v_pk_mul_f32 v[6:7], v[114:115], v[6:7]
	v_pk_mul_f32 v[8:9], v[114:115], v[8:9]
	v_pk_mul_f32 v[10:11], v[114:115], v[10:11]
	v_pk_mul_f32 v[12:13], v[114:115], v[12:13]
	v_pk_mul_f32 v[14:15], v[114:115], v[14:15]
	v_mad_i64_i32 v[114:115], s[2:3], v33, s36, v[110:111]
	v_mov_b32_e32 v47, v46
	v_mad_u64_u32 v[70:71], s[2:3], v114, s76, v[108:109]
	v_lshlrev_b64 v[66:67], 7, v[114:115]
	v_mad_i32_i24 v71, v115, s76, v71
	v_pk_mul_f32 v[114:115], v[124:125], v[46:47]
	v_pk_mul_f32 v[118:119], v[118:119], v[46:47]
	v_pk_mul_f32 v[48:49], v[48:49], v[46:47]
	v_pk_mul_f32 v[54:55], v[54:55], v[46:47]
	v_pk_mul_f32 v[60:61], v[60:61], v[46:47]
	v_pk_mul_f32 v[56:57], v[56:57], v[46:47]
	v_pk_mul_f32 v[40:41], v[40:41], v[46:47]
	v_lshl_add_u64 v[66:67], s[0:1], 0, v[66:67]
	v_cvt_pk_bf16_f32 v16, v16, v17
	v_cvt_pk_bf16_f32 v17, v18, v19
	v_cvt_pk_bf16_f32 v18, v20, v21
	v_cvt_pk_bf16_f32 v20, v24, v25
	v_lshl_add_u64 v[24:25], v[66:67], 0, v[80:81]
	s_mov_b64 s[2:3], 0x1b456100
	v_cvt_pk_bf16_f32 v21, v26, v27
	v_lshl_add_u64 v[26:27], v[24:25], 0, s[2:3]
	s_mov_b32 s2, 0x1b456000
	v_cvt_pk_bf16_f32 v19, v22, v23
	v_cvt_pk_bf16_f32 v22, v28, v29
	v_add_co_u32_e32 v28, vcc, s2, v24
	v_permlane32_swap_b32_e32 v16, v18
	v_permlane32_swap_b32_e32 v17, v19
	v_addc_co_u32_e32 v29, vcc, 0, v25, vcc
	v_cvt_pk_bf16_f32 v33, v72, v73
	v_cvt_pk_bf16_f32 v35, v36, v37
	v_cvt_pk_bf16_f32 v23, v30, v31
	s_mov_b64 s[2:3], 0x1b456140
	v_permlane32_swap_b32_e32 v33, v35
	v_permlane32_swap_b32_e32 v20, v22
	v_permlane32_swap_b32_e32 v21, v23
	s_waitcnt vmcnt(0)
	v_pk_mul_f32 v[124:125], v[114:115], v[130:131]
	v_pk_mul_f32 v[114:115], v[120:121], v[46:47]
	s_nop 0
	v_pk_mul_f32 v[130:131], v[114:115], v[132:133]
	v_pk_mul_f32 v[114:115], v[122:123], v[46:47]
	v_pk_mul_f32 v[120:121], v[114:115], v[216:217]
	v_pk_mul_f32 v[114:115], v[116:117], v[46:47]
	s_nop 0
	v_pk_mul_f32 v[122:123], v[114:115], v[218:219]
	v_pk_mul_f32 v[118:119], v[118:119], v[220:221]
	v_pk_mul_f32 v[48:49], v[48:49], v[222:223]
	v_cvt_pk_bf16_f32 v118, v118, v119
	v_cvt_pk_bf16_f32 v119, v48, v49
	v_pk_mul_f32 v[54:55], v[54:55], v[224:225]
	v_pk_mul_f32 v[60:61], v[60:61], v[226:227]
	v_cvt_pk_bf16_f32 v114, v124, v125
	v_cvt_pk_bf16_f32 v115, v130, v131
	v_cvt_pk_bf16_f32 v116, v120, v121
	v_cvt_pk_bf16_f32 v117, v122, v123
	v_cvt_pk_bf16_f32 v120, v54, v55
	v_cvt_pk_bf16_f32 v121, v60, v61
	v_permlane32_swap_b32_e32 v114, v116
	v_permlane32_swap_b32_e32 v115, v117
	v_permlane32_swap_b32_e32 v118, v120
	v_permlane32_swap_b32_e32 v119, v121
	flat_store_dwordx4 v[70:71], v[114:117]
	flat_store_dwordx4 v[70:71], v[118:121] offset:32
	v_pk_mul_f32 v[54:55], v[50:51], v[46:47]
	v_pk_mul_f32 v[54:55], v[54:55], v[228:229]
	v_pk_mul_f32 v[48:49], v[52:53], v[46:47]
	s_nop 0
	v_pk_mul_f32 v[52:53], v[48:49], v[230:231]
	v_pk_mul_f32 v[56:57], v[56:57], v[232:233]
	v_pk_mul_f32 v[48:49], v[58:59], v[46:47]
	s_nop 0
	v_pk_mul_f32 v[58:59], v[48:49], v[234:235]
	v_pk_mul_f32 v[60:61], v[40:41], v[236:237]
	v_pk_mul_f32 v[40:41], v[62:63], v[46:47]
	s_nop 0
	v_pk_mul_f32 v[62:63], v[40:41], v[238:239]
	v_pk_mul_f32 v[40:41], v[44:45], v[46:47]
	v_cvt_pk_bf16_f32 v44, v60, v61
	v_cvt_pk_bf16_f32 v45, v62, v63
	v_pk_mul_f32 v[48:49], v[40:41], v[244:245]
	v_pk_mul_f32 v[40:41], v[42:43], v[46:47]
	v_cvt_pk_bf16_f32 v42, v56, v57
	v_pk_mul_f32 v[50:51], v[40:41], v[246:247]
	v_cvt_pk_bf16_f32 v40, v54, v55
	v_cvt_pk_bf16_f32 v41, v52, v53
	v_cvt_pk_bf16_f32 v43, v58, v59
	v_permlane32_swap_b32_e32 v40, v42
	s_nop 0
	v_permlane32_swap_b32_e32 v41, v43
	flat_store_dwordx4 v[70:71], v[40:43] offset:64
	v_cvt_pk_bf16_f32 v46, v48, v49
	v_cvt_pk_bf16_f32 v47, v50, v51
	v_cvt_pk_bf16_f32 v40, v76, v128
	v_cvt_pk_bf16_f32 v41, v78, v74
	v_cvt_pk_bf16_f32 v42, v32, v68
	v_cvt_pk_bf16_f32 v43, v34, v38
	s_nop 0
	v_permlane32_swap_b32_e32 v40, v42
	v_permlane32_swap_b32_e32 v41, v43
	v_cvt_pk_bf16_f32 v32, v126, v127
	v_cvt_pk_bf16_f32 v34, v64, v65
	flat_store_dwordx4 v[70:71], v[40:43] offset:128
	flat_store_dwordx4 v[28:29], v[16:19] offset:256
	v_permlane32_swap_b32_e32 v44, v46
	s_nop 0
	v_cvt_pk_bf16_f32 v16, v0, v1
	v_cvt_pk_bf16_f32 v17, v2, v3
	v_cvt_pk_bf16_f32 v18, v4, v5
	v_cvt_pk_bf16_f32 v19, v6, v7
	v_cvt_pk_bf16_f32 v0, v8, v9
	v_cvt_pk_bf16_f32 v1, v10, v11
	v_cvt_pk_bf16_f32 v2, v12, v13
	v_cvt_pk_bf16_f32 v3, v14, v15
	v_permlane32_swap_b32_e32 v45, v47
	v_permlane32_swap_b32_e32 v32, v34
	v_lshl_add_u64 v[4:5], v[24:25], 0, s[2:3]
	v_permlane32_swap_b32_e32 v16, v18
	v_permlane32_swap_b32_e32 v17, v19
	v_permlane32_swap_b32_e32 v0, v2
	v_permlane32_swap_b32_e32 v1, v3
	flat_store_dwordx4 v[70:71], v[44:47] offset:96
	flat_store_dwordx4 v[70:71], v[32:35] offset:160
	flat_store_dwordx4 v[26:27], v[20:23] offset:32
	flat_store_dwordx4 v[28:29], v[16:19] offset:320
	flat_store_dwordx4 v[4:5], v[0:3] offset:32
	s_branch .LBB0_335
